# grid barrier: waiters poll the monotonic TOP arrival counter instead of TOPGEN (8 of 10 barrier sites), on top of nt4
# baseline (speedup 1.0000x reference)
; __device__ __forceinline__ unsigned xb_ld(unsigned* p)              { return __hip_atomic_load(p, __ATOMIC_RELAXED, __HIP_MEMORY_SCOPE_AGENT); }
; __device__ __forceinline__ unsigned xb_add(unsigned* p, unsigned v) { return __hip_atomic_fetch_add(p, v, __ATOMIC_RELAXED, __HIP_MEMORY_SCOPE_AGENT); }
; #define XB_SPIN(cond, bar) do { unsigned _sp = 0; while (cond) { __builtin_amdgcn_s_sleep(1); \
;     if ((++_sp & 255u) == 0u) { if (xb_ld(&(bar)[XB_TMO])) break; if (_sp > XB_SPIN_CAP) { atomicAdd(&(bar)[XB_TMO], 1u); break; } } } } while (0)
; __device__ __forceinline__ void xcd_barrier(const XcdBarrier& b) {
;     ...
;         const unsigned old = xb_add(&bar[XB_XSUB(b.x)], 1u);
;         const unsigned gen = old / nloc;
;         if (old + 1u == (gen + 1u) * nloc) {
;             __builtin_amdgcn_fence(__ATOMIC_RELEASE, "agent");
;             asm volatile("s_waitcnt vmcnt(0)" ::: "memory");
;             const unsigned og = xb_add(&bar[XB_TOP], 1u);
;             const unsigned tg = og / nx;
;             if (og + 1u == (tg + 1u) * nx) xb_add(&bar[XB_TOPGEN], 1u);
;             else XB_SPIN(xb_ld(&bar[XB_TOPGEN]) == tg, bar);
;             __builtin_amdgcn_fence(__ATOMIC_ACQUIRE, "agent");
;             asm volatile("s_waitcnt vmcnt(0)" ::: "memory");
;         } else {
;             XB_SPIN(xb_ld(&bar[XB_TOPGEN]) == gen, bar);
;             __builtin_amdgcn_fence(__ATOMIC_ACQUIRE, "agent");
;             asm volatile("s_waitcnt vmcnt(0)" ::: "memory");
.LBB0_214:
	s_or_b64 exec, exec, s[6:7]
	v_cvt_f32_u32_e32 v4, v2
	s_waitcnt vmcnt(0)
	v_readfirstlane_b32 s6, v3
	v_sub_u32_e32 v3, 0, v2
	v_rcp_iflag_f32_e32 v4, v4
	v_add_u32_e32 v5, s6, v1
	v_mul_f32_e32 v4, 0x4f7ffffe, v4
	v_cvt_u32_f32_e32 v4, v4
	v_mul_lo_u32 v1, v3, v4
	v_mul_hi_u32 v1, v4, v1
	v_add_u32_e32 v1, v4, v1
	v_mul_hi_u32 v1, v5, v1
	v_mul_lo_u32 v3, v1, v2
	v_sub_u32_e32 v3, v5, v3
	v_add_u32_e32 v4, 1, v1
	v_cmp_ge_u32_e32 vcc, v3, v2
	s_nop 1
	v_cndmask_b32_e32 v1, v1, v4, vcc
	v_sub_u32_e32 v4, v3, v2
	v_cndmask_b32_e32 v3, v3, v4, vcc
	v_add_u32_e32 v4, 1, v1
	v_cmp_ge_u32_e32 vcc, v3, v2
	v_add_u32_e32 v3, 1, v5
	s_nop 0
	v_cndmask_b32_e32 v1, v1, v4, vcc
	v_mul_lo_u32 v4, v2, v1
	v_add_u32_e32 v2, v4, v2
	v_cmp_ne_u32_e32 vcc, v3, v2
	s_and_saveexec_b64 s[6:7], vcc
	s_xor_b64 s[6:7], exec, s[6:7]
	s_cbranch_execz .LBB0_228
	s_waitcnt lgkmcnt(0)
	v_mad_u32_u24 v5, v1, v0, v0
	global_load_dword v0, v185, s[4:5] offset:1024 sc1
	s_add_u32 s10, s4, 0x3400
	s_addc_u32 s11, s5, 0
	s_waitcnt vmcnt(0)
	v_cmp_lt_u32_e32 vcc, v0, v5
	s_and_saveexec_b64 s[8:9], vcc
	s_cbranch_execz .LBB0_227
	s_mov_b32 s19, 1
	s_mov_b64 s[12:13], 0
	s_branch .LBB0_218

; __device__ __forceinline__ unsigned xb_ld(unsigned* p)              { return __hip_atomic_load(p, __ATOMIC_RELAXED, __HIP_MEMORY_SCOPE_AGENT); }
; #define XB_SPIN(cond, bar) do { unsigned _sp = 0; while (cond) { __builtin_amdgcn_s_sleep(1); \
;     if ((++_sp & 255u) == 0u) { if (xb_ld(&(bar)[XB_TMO])) break; if (_sp > XB_SPIN_CAP) { atomicAdd(&(bar)[XB_TMO], 1u); break; } } } } while (0)
; __device__ __forceinline__ void xcd_barrier(const XcdBarrier& b) {
;     ...
;             else XB_SPIN(xb_ld(&bar[XB_TOPGEN]) == tg, bar);
;             __builtin_amdgcn_fence(__ATOMIC_ACQUIRE, "agent");
;             asm volatile("s_waitcnt vmcnt(0)" ::: "memory");
;         } else {
;             XB_SPIN(xb_ld(&bar[XB_TOPGEN]) == gen, bar);
.LBB0_220:
	global_load_dword v0, v161, s[10:11] sc1
	s_add_i32 s19, s19, 1
	s_mov_b64 s[30:31], -1
	s_waitcnt vmcnt(0)
	v_cmp_ge_u32_e32 vcc, v0, v5
	s_orn2_b64 s[16:17], vcc, exec
	s_branch .LBB0_217

; __device__ __forceinline__ unsigned xb_ld(unsigned* p)              { return __hip_atomic_load(p, __ATOMIC_RELAXED, __HIP_MEMORY_SCOPE_AGENT); }
; __device__ __forceinline__ unsigned xb_add(unsigned* p, unsigned v) { return __hip_atomic_fetch_add(p, v, __ATOMIC_RELAXED, __HIP_MEMORY_SCOPE_AGENT); }
; #define XB_SPIN(cond, bar) do { unsigned _sp = 0; while (cond) { __builtin_amdgcn_s_sleep(1); \
;     if ((++_sp & 255u) == 0u) { if (xb_ld(&(bar)[XB_TMO])) break; if (_sp > XB_SPIN_CAP) { atomicAdd(&(bar)[XB_TMO], 1u); break; } } } } while (0)
; __device__ __forceinline__ void xcd_barrier(const XcdBarrier& b) {
;     ...
;             __builtin_amdgcn_fence(__ATOMIC_RELEASE, "agent");
;             asm volatile("s_waitcnt vmcnt(0)" ::: "memory");
;             const unsigned og = xb_add(&bar[XB_TOP], 1u);
;             const unsigned tg = og / nx;
;             if (og + 1u == (tg + 1u) * nx) xb_add(&bar[XB_TOPGEN], 1u);
;             else XB_SPIN(xb_ld(&bar[XB_TOPGEN]) == tg, bar);
.LBB0_231:
	s_or_b64 exec, exec, s[8:9]
	s_waitcnt vmcnt(0)
	v_readfirstlane_b32 s6, v2
	v_cvt_f32_u32_e32 v2, v0
	v_sub_u32_e32 v3, 0, v0
	v_add_u32_e32 v1, s6, v1
	s_add_u32 s6, s4, 0x3500
	v_rcp_iflag_f32_e32 v2, v2
	s_addc_u32 s7, s5, 0
	s_mov_b64 s[10:11], -1
	v_mul_f32_e32 v2, 0x4f7ffffe, v2
	v_cvt_u32_f32_e32 v2, v2
	v_mul_lo_u32 v3, v3, v2
	v_mul_hi_u32 v3, v2, v3
	v_add_u32_e32 v2, v2, v3
	v_mul_hi_u32 v2, v1, v2
	v_mul_lo_u32 v3, v2, v0
	v_sub_u32_e32 v3, v1, v3
	v_cmp_ge_u32_e32 vcc, v3, v0
	v_add_u32_e32 v4, 1, v2
	v_add_u32_e32 v1, 1, v1
	v_cndmask_b32_e32 v2, v2, v4, vcc
	v_sub_u32_e32 v4, v3, v0
	v_cndmask_b32_e32 v3, v3, v4, vcc
	v_cmp_ge_u32_e32 vcc, v3, v0
	v_add_u32_e32 v3, 1, v2
	s_nop 0
	v_cndmask_b32_e32 v2, v2, v3, vcc
	v_mul_lo_u32 v3, v0, v2
	v_add_u32_e32 v0, v3, v0
	v_mov_b32_e32 v5, v0
	v_cmp_ne_u32_e32 vcc, v1, v0
	v_mov_b64_e32 v[0:1], s[6:7]
	s_and_saveexec_b64 s[8:9], vcc
	s_cbranch_execz .LBB0_243
	global_load_dword v0, v185, s[4:5] offset:1024 sc1
	s_mov_b64 s[14:15], 0
	s_waitcnt vmcnt(0)
	v_cmp_lt_u32_e32 vcc, v0, v5
	s_and_saveexec_b64 s[12:13], vcc
	s_cbranch_execz .LBB0_242
	s_add_u32 s10, s4, 0x200
	s_addc_u32 s11, s5, 0
	s_mov_b32 s19, 1
	s_mov_b64 s[4:5], 0
	s_branch .LBB0_235

; __device__ __forceinline__ unsigned xb_ld(unsigned* p)              { return __hip_atomic_load(p, __ATOMIC_RELAXED, __HIP_MEMORY_SCOPE_AGENT); }
; __device__ __forceinline__ unsigned xb_add(unsigned* p, unsigned v) { return __hip_atomic_fetch_add(p, v, __ATOMIC_RELAXED, __HIP_MEMORY_SCOPE_AGENT); }
; #define XB_SPIN(cond, bar) do { unsigned _sp = 0; while (cond) { __builtin_amdgcn_s_sleep(1); \
;     if ((++_sp & 255u) == 0u) { if (xb_ld(&(bar)[XB_TMO])) break; if (_sp > XB_SPIN_CAP) { atomicAdd(&(bar)[XB_TMO], 1u); break; } } } } while (0)
; __device__ __forceinline__ void xcd_barrier(const XcdBarrier& b) {
;     ...
;             const unsigned og = xb_add(&bar[XB_TOP], 1u);
;             const unsigned tg = og / nx;
;             if (og + 1u == (tg + 1u) * nx) xb_add(&bar[XB_TOPGEN], 1u);
;             else XB_SPIN(xb_ld(&bar[XB_TOPGEN]) == tg, bar);
.LBB0_237:
	global_load_dword v0, v185, s[10:11] offset:512 sc1
	s_add_i32 s19, s19, 1
	s_mov_b64 s[30:31], -1
	s_waitcnt vmcnt(0)
	v_cmp_ge_u32_e32 vcc, v0, v5
	s_orn2_b64 s[16:17], vcc, exec
	s_branch .LBB0_234
